# attention loops: packed fp32 VOP3P ops between the PV MFMAs split into scalar v_fma/v_add pairs (bit-identical)
# baseline (speedup 1.0000x reference)
.LBB0_356:
	v_fma_f32 v14, v64, s8, -v120
	v_fma_f32 v15, v65, s8, -v120
	v_fma_f32 v48, v48, s8, -v120
	v_fma_f32 v49, v49, s8, -v120
	v_exp_f32_e32 v14, v14
	v_exp_f32_e32 v15, v15
	v_exp_f32_e32 v132, v48
	v_exp_f32_e32 v133, v49
	v_fma_f32 v48, v66, s8, -v120
	v_fma_f32 v49, v67, s8, -v120
	v_fma_f32 v50, v50, s8, -v120
	v_fma_f32 v51, v51, s8, -v120
	v_exp_f32_e32 v64, v48
	v_exp_f32_e32 v65, v49
	v_exp_f32_e32 v134, v50
	v_exp_f32_e32 v135, v51
	v_fma_f32 v50, v68, s8, -v120
	v_fma_f32 v51, v69, s8, -v120
	v_add_f32_e64 v48, v14, 0
	v_add_f32_e64 v49, v15, 0
	v_exp_f32_e32 v66, v50
	v_exp_f32_e32 v67, v51
	v_add_f32_e32 v48, v132, v48
	v_add_f32_e32 v49, v133, v49
	s_mul_i32 s13, s12, 0x2200
	v_add_f32_e32 v48, v64, v48
	v_add_f32_e32 v49, v65, v49
	v_fma_f32 v50, v52, s8, -v120
	v_fma_f32 v51, v53, s8, -v120
	v_add_f32_e32 v48, v134, v48
	v_add_f32_e32 v49, v135, v49
	v_add_u32_e32 v0, s13, v130
	v_exp_f32_e32 v68, v50
	v_exp_f32_e32 v69, v51
	v_add_f32_e32 v136, v66, v48
	v_add_f32_e32 v137, v67, v49
	v_fma_f32 v48, v70, s8, -v120
	v_fma_f32 v49, v71, s8, -v120
	v_fma_f32 v50, v54, s8, -v120
	v_fma_f32 v51, v55, s8, -v120
	v_add_u32_e32 v140, 0x4800, v0
	v_exp_f32_e32 v70, v48
	v_exp_f32_e32 v71, v49
	v_exp_f32_e32 v138, v50
	v_exp_f32_e32 v139, v51
	ds_read2_b64 v[48:51], v140 offset1:2
	v_fma_f32 v52, v72, s8, -v120
	v_fma_f32 v53, v73, s8, -v120
	v_cvt_pk_bf16_f32 v54, v66, v67
	v_exp_f32_e32 v72, v52
	v_exp_f32_e32 v73, v53
	v_cvt_pk_bf16_f32 v52, v14, v15
	v_cvt_pk_bf16_f32 v53, v64, v65
	v_cvt_pk_bf16_f32 v55, v70, v71
	v_add_u32_e32 v0, 0x5800, v0
	v_fma_f32 v74, v74, s8, -v120
	v_fma_f32 v75, v75, s8, -v120
	ds_read2_b64 v[64:67], v0 offset0:32 offset1:34
	s_waitcnt lgkmcnt(1)
	v_mfma_f32_32x32x16_bf16 v[32:47], v[48:51], v[52:55], v[32:47]
	v_fma_f32 v48, v76, s8, -v120
	v_fma_f32 v49, v77, s8, -v120
	v_exp_f32_e32 v14, v74
	v_exp_f32_e32 v15, v75
	v_exp_f32_e32 v74, v48
	v_exp_f32_e32 v75, v49
	ds_read2_b64 v[48:51], v140 offset0:4 offset1:6
	v_fma_f32 v76, v78, s8, -v120
	v_fma_f32 v77, v79, s8, -v120
	s_waitcnt lgkmcnt(1)
	v_mfma_f32_32x32x16_bf16 v[16:31], v[64:67], v[52:55], v[16:31]
	v_exp_f32_e32 v76, v76
	v_exp_f32_e32 v77, v77
	v_cvt_pk_bf16_f32 v52, v72, v73
	v_cvt_pk_bf16_f32 v53, v14, v15
	v_cvt_pk_bf16_f32 v54, v74, v75
	v_cvt_pk_bf16_f32 v55, v76, v77
	ds_read2_b64 v[64:67], v0 offset0:36 offset1:38
	v_fma_f32 v62, v62, s8, -v120
	v_fma_f32 v63, v63, s8, -v120
	s_waitcnt lgkmcnt(1)
	v_mfma_f32_32x32x16_bf16 v[32:47], v[48:51], v[52:55], v[32:47]
	v_add_f32_e64 v48, v68, v136
	v_add_f32_e64 v49, v69, v137
	v_exp_f32_e32 v62, v62
	v_add_f32_e32 v48, v70, v48
	v_add_f32_e32 v49, v71, v49
	v_exp_f32_e32 v63, v63
	v_add_f32_e32 v70, v138, v48
	v_add_f32_e32 v71, v139, v49
	v_fma_f32 v48, v56, s8, -v120
	v_fma_f32 v49, v57, s8, -v120
	s_xor_b32 s12, s12, 1
	v_exp_f32_e32 v78, v48
	v_exp_f32_e32 v79, v49
	ds_read2_b64 v[48:51], v140 offset0:8 offset1:10
	s_waitcnt lgkmcnt(1)
	v_mfma_f32_32x32x16_bf16 v[16:31], v[64:67], v[52:55], v[16:31]
	v_cvt_pk_bf16_f32 v52, v132, v133
	v_cvt_pk_bf16_f32 v53, v134, v135
	v_cvt_pk_bf16_f32 v54, v68, v69
	v_cvt_pk_bf16_f32 v55, v138, v139
	v_fma_f32 v66, v58, s8, -v120
	v_fma_f32 v67, v59, s8, -v120
	ds_read2_b64 v[56:59], v0 offset0:40 offset1:42
	v_exp_f32_e32 v66, v66
	s_waitcnt lgkmcnt(1)
	v_mfma_f32_32x32x16_bf16 v[32:47], v[48:51], v[52:55], v[32:47]
	v_fma_f32 v48, v60, s8, -v120
	v_fma_f32 v49, v61, s8, -v120
	v_exp_f32_e32 v67, v67
	v_exp_f32_e32 v60, v48
	v_exp_f32_e32 v61, v49
	ds_read2_b64 v[48:51], v140 offset0:12 offset1:14
	v_add_f32_e32 v64, v72, v70
	v_add_f32_e32 v65, v73, v71
	s_mul_i32 s13, s12, 0x2400
	s_waitcnt lgkmcnt(1)
	v_mfma_f32_32x32x16_bf16 v[16:31], v[56:59], v[52:55], v[16:31]
	v_cvt_pk_bf16_f32 v52, v78, v79
	v_cvt_pk_bf16_f32 v53, v66, v67
	v_cvt_pk_bf16_f32 v54, v60, v61
	v_cvt_pk_bf16_f32 v55, v62, v63
	ds_read2_b64 v[56:59], v0 offset0:44 offset1:46
	s_mulk_i32 s12, 0x2200
	s_add_u32 s10, s10, 0x8000
	s_waitcnt lgkmcnt(1)
	v_mfma_f32_32x32x16_bf16 v[32:47], v[48:51], v[52:55], v[32:47]
	v_add_f32_e64 v48, v78, v64
	v_add_f32_e64 v49, v79, v65
	s_addc_u32 s11, s11, 0
	v_add_f32_e64 v14, v14, v48
	v_add_f32_e64 v15, v15, v49
	s_add_i32 s21, s21, 1
	v_add_f32_e32 v14, v66, v14
	v_add_f32_e32 v15, v67, v15
	s_cmp_eq_u32 s22, s10
	v_add_f32_e32 v14, v74, v14
	v_add_f32_e32 v15, v75, v15
	s_waitcnt lgkmcnt(0)
	v_mfma_f32_32x32x16_bf16 v[16:31], v[56:59], v[52:55], v[16:31]
	v_add_f32_e64 v14, v60, v14
	v_add_f32_e64 v15, v61, v15
	v_add_f32_e64 v14, v76, v14
	v_add_f32_e64 v15, v77, v15
	v_add_f32_e64 v14, v62, v14
	v_add_f32_e64 v15, v63, v15
	v_add_f32_e32 v0, v14, v15
	v_add_f32_e32 v115, v115, v0
	v_add_u32_e32 v0, s13, v126
	s_waitcnt vmcnt(3)
	ds_write_b128 v0, v[10:13]
	s_waitcnt vmcnt(2)
	ds_write_b128 v0, v[96:99] offset:4608
	v_add_u32_e32 v0, s12, v127
	s_waitcnt vmcnt(1)
	v_and_b32_e32 v10, 0xffff, v2
	v_lshrrev_b32_e32 v2, 16, v2
	s_waitcnt vmcnt(0)
	v_lshl_or_b32 v10, v6, 16, v10
	v_and_or_b32 v2, v6, s18, v2
	v_add_u32_e32 v0, 0x4800, v0
	ds_write2_b32 v0, v10, v2 offset1:34
	v_and_b32_e32 v2, 0xffff, v3
	v_lshrrev_b32_e32 v3, 16, v3
	v_lshl_or_b32 v2, v7, 16, v2
	v_and_or_b32 v3, v7, s18, v3
	ds_write2_b32 v0, v2, v3 offset0:68 offset1:102
	v_and_b32_e32 v2, 0xffff, v4
	v_lshrrev_b32_e32 v3, 16, v4
	v_lshl_or_b32 v2, v8, 16, v2
	v_and_or_b32 v3, v8, s18, v3
	ds_write2_b32 v0, v2, v3 offset0:136 offset1:170
	v_and_b32_e32 v2, 0xffff, v5
	v_lshrrev_b32_e32 v3, 16, v5
	v_lshl_or_b32 v2, v9, 16, v2
	v_and_or_b32 v3, v9, s18, v3
	ds_write2_b32 v0, v2, v3 offset0:204 offset1:238
	s_waitcnt lgkmcnt(0)
	s_barrier
	s_cbranch_scc1 .LBB0_348

.LBB0_2452:
	v_fma_f32 v48, v48, s16, -v138
	v_fma_f32 v49, v49, s16, -v138
	v_fma_f32 v32, v32, s16, -v138
	v_fma_f32 v33, v33, s16, -v138
	v_exp_f32_e32 v48, v48
	v_exp_f32_e32 v49, v49
	v_exp_f32_e32 v150, v32
	v_exp_f32_e32 v151, v33
	v_fma_f32 v32, v50, s16, -v138
	v_fma_f32 v33, v51, s16, -v138
	v_fma_f32 v34, v34, s16, -v138
	v_fma_f32 v35, v35, s16, -v138
	v_exp_f32_e32 v50, v32
	v_exp_f32_e32 v51, v33
	v_exp_f32_e32 v152, v34
	v_exp_f32_e32 v153, v35
	v_fma_f32 v34, v52, s16, -v138
	v_fma_f32 v35, v53, s16, -v138
	v_add_f32_e64 v32, v48, 0
	v_add_f32_e64 v33, v49, 0
	v_exp_f32_e32 v52, v34
	v_exp_f32_e32 v53, v35
	v_add_f32_e32 v32, v150, v32
	v_add_f32_e32 v33, v151, v33
	s_mul_i32 s23, s22, 0x2200
	v_add_f32_e32 v32, v50, v32
	v_add_f32_e32 v33, v51, v33
	v_fma_f32 v34, v36, s16, -v138
	v_fma_f32 v35, v37, s16, -v138
	v_add_f32_e32 v32, v152, v32
	v_add_f32_e32 v33, v153, v33
	v_add_u32_e32 v160, s23, v147
	v_exp_f32_e32 v154, v34
	v_exp_f32_e32 v155, v35
	v_add_f32_e32 v156, v52, v32
	v_add_f32_e32 v157, v53, v33
	v_fma_f32 v32, v54, s16, -v138
	v_fma_f32 v33, v55, s16, -v138
	v_fma_f32 v34, v38, s16, -v138
	v_fma_f32 v35, v39, s16, -v138
	v_add_u32_e32 v161, 0x6800, v160
	v_exp_f32_e32 v54, v32
	v_exp_f32_e32 v55, v33
	v_exp_f32_e32 v158, v34
	v_exp_f32_e32 v159, v35
	ds_read2_b64 v[32:35], v161 offset1:2
	v_fma_f32 v36, v56, s16, -v138
	v_fma_f32 v37, v57, s16, -v138
	v_cvt_pk_bf16_f32 v38, v52, v53
	v_exp_f32_e32 v56, v36
	v_exp_f32_e32 v57, v37
	v_cvt_pk_bf16_f32 v36, v48, v49
	v_cvt_pk_bf16_f32 v37, v50, v51
	v_cvt_pk_bf16_f32 v39, v54, v55
	v_add_u32_e32 v160, 0x7800, v160
	v_fma_f32 v58, v58, s16, -v138
	v_fma_f32 v59, v59, s16, -v138
	ds_read2_b64 v[48:51], v160 offset0:32 offset1:34
	s_waitcnt lgkmcnt(1)
	v_mfma_f32_32x32x16_bf16 v[16:31], v[32:35], v[36:39], v[16:31]
	v_fma_f32 v32, v60, s16, -v138
	v_fma_f32 v33, v61, s16, -v138
	v_exp_f32_e32 v52, v58
	v_exp_f32_e32 v53, v59
	v_exp_f32_e32 v58, v32
	v_exp_f32_e32 v59, v33
	ds_read2_b64 v[32:35], v161 offset0:4 offset1:6
	v_fma_f32 v60, v62, s16, -v138
	v_fma_f32 v61, v63, s16, -v138
	s_waitcnt lgkmcnt(1)
	v_mfma_f32_32x32x16_bf16 v[0:15], v[48:51], v[36:39], v[0:15]
	v_exp_f32_e32 v60, v60
	v_exp_f32_e32 v61, v61
	v_cvt_pk_bf16_f32 v36, v56, v57
	v_cvt_pk_bf16_f32 v37, v52, v53
	v_cvt_pk_bf16_f32 v38, v58, v59
	v_cvt_pk_bf16_f32 v39, v60, v61
	ds_read2_b64 v[48:51], v160 offset0:36 offset1:38
	v_fma_f32 v46, v46, s16, -v138
	v_fma_f32 v47, v47, s16, -v138
	s_waitcnt lgkmcnt(1)
	v_mfma_f32_32x32x16_bf16 v[16:31], v[32:35], v[36:39], v[16:31]
	v_add_f32_e64 v32, v154, v156
	v_add_f32_e64 v33, v155, v157
	v_exp_f32_e32 v46, v46
	v_add_f32_e32 v32, v54, v32
	v_add_f32_e32 v33, v55, v33
	v_exp_f32_e32 v47, v47
	v_add_f32_e32 v54, v158, v32
	v_add_f32_e32 v55, v159, v33
	v_fma_f32 v32, v40, s16, -v138
	v_fma_f32 v33, v41, s16, -v138
	s_xor_b32 s22, s22, 1
	v_exp_f32_e32 v62, v32
	v_exp_f32_e32 v63, v33
	ds_read2_b64 v[32:35], v161 offset0:8 offset1:10
	s_waitcnt lgkmcnt(1)
	v_mfma_f32_32x32x16_bf16 v[0:15], v[48:51], v[36:39], v[0:15]
	v_cvt_pk_bf16_f32 v36, v150, v151
	v_cvt_pk_bf16_f32 v37, v152, v153
	v_cvt_pk_bf16_f32 v38, v154, v155
	v_cvt_pk_bf16_f32 v39, v158, v159
	v_fma_f32 v50, v42, s16, -v138
	v_fma_f32 v51, v43, s16, -v138
	ds_read2_b64 v[40:43], v160 offset0:40 offset1:42
	v_exp_f32_e32 v50, v50
	s_waitcnt lgkmcnt(1)
	v_mfma_f32_32x32x16_bf16 v[16:31], v[32:35], v[36:39], v[16:31]
	v_fma_f32 v32, v44, s16, -v138
	v_fma_f32 v33, v45, s16, -v138
	v_exp_f32_e32 v51, v51
	v_exp_f32_e32 v44, v32
	v_exp_f32_e32 v45, v33
	ds_read2_b64 v[32:35], v161 offset0:12 offset1:14
	v_add_f32_e32 v48, v56, v54
	v_add_f32_e32 v49, v57, v55
	s_mul_i32 s23, s22, 0x3400
	s_waitcnt lgkmcnt(1)
	v_mfma_f32_32x32x16_bf16 v[0:15], v[40:43], v[36:39], v[0:15]
	v_cvt_pk_bf16_f32 v36, v62, v63
	v_cvt_pk_bf16_f32 v37, v50, v51
	v_cvt_pk_bf16_f32 v38, v44, v45
	v_cvt_pk_bf16_f32 v39, v46, v47
	ds_read2_b64 v[40:43], v160 offset0:44 offset1:46
	s_add_i32 s23, s23, 32
	s_mulk_i32 s22, 0x2200
	s_waitcnt lgkmcnt(1)
	v_mfma_f32_32x32x16_bf16 v[16:31], v[32:35], v[36:39], v[16:31]
	v_add_f32_e64 v32, v62, v48
	v_add_f32_e64 v33, v63, v49
	s_waitcnt vmcnt(1)
	v_lshrrev_b32_e32 v34, 16, v88
	v_add_f32_e64 v32, v52, v32
	v_add_f32_e64 v33, v53, v33
	s_waitcnt vmcnt(0)
	v_and_or_b32 v34, v92, s36, v34
	v_add_f32_e32 v32, v50, v32
	v_add_f32_e32 v33, v51, v33
	s_add_i32 s27, s27, 1
	v_add_f32_e32 v32, v58, v32
	v_add_f32_e32 v33, v59, v33
	s_waitcnt lgkmcnt(0)
	v_mfma_f32_32x32x16_bf16 v[0:15], v[40:43], v[36:39], v[0:15]
	v_add_f32_e64 v32, v44, v32
	v_add_f32_e64 v33, v45, v33
	v_lshl_add_u64 v[134:135], v[134:135], 0, s[18:19]
	v_add_f32_e64 v32, v60, v32
	v_add_f32_e64 v33, v61, v33
	v_lshl_add_u64 v[136:137], v[136:137], 0, s[18:19]
	v_add_f32_e32 v32, v46, v32
	v_add_f32_e32 v33, v47, v33
	s_cmp_eq_u32 s24, s27
	v_add_f32_e32 v32, v32, v33
	v_add_f32_e32 v149, v149, v32
	v_add3_u32 v32, s23, v140, v124
	ds_write_b128 v32, v[96:99]
	ds_write_b128 v32, v[100:103] offset:6656
	v_add3_u32 v32, s23, v142, v126
	ds_write_b128 v32, v[104:107] offset:128
	v_add_u32_e32 v32, s22, v144
	v_and_b32_e32 v33, 0xffff, v88
	v_lshl_or_b32 v33, v92, 16, v33
	v_add_u32_e32 v32, 0x6800, v32
	ds_write2_b32 v32, v33, v34 offset1:34
	v_and_b32_e32 v33, 0xffff, v89
	v_lshrrev_b32_e32 v34, 16, v89
	v_lshl_or_b32 v33, v93, 16, v33
	v_and_or_b32 v34, v93, s36, v34
	ds_write2_b32 v32, v33, v34 offset0:68 offset1:102
	v_and_b32_e32 v33, 0xffff, v90
	v_lshrrev_b32_e32 v34, 16, v90
	v_lshl_or_b32 v33, v94, 16, v33
	v_and_or_b32 v34, v94, s36, v34
	ds_write2_b32 v32, v33, v34 offset0:136 offset1:170
	v_and_b32_e32 v33, 0xffff, v91
	v_lshrrev_b32_e32 v34, 16, v91
	v_lshl_or_b32 v33, v95, 16, v33
	v_and_or_b32 v34, v95, s36, v34
	v_lshl_add_u64 v[132:133], v[132:133], 0, s[20:21]
	ds_write2_b32 v32, v33, v34 offset0:204 offset1:238
	s_waitcnt lgkmcnt(0)
	s_barrier
	s_cbranch_scc1 .LBB0_2444
